# SSM-out gate hook: agent acquire (L1 invalidate) issued before the flag poll so it overlaps the wait
# baseline (speedup 1.0000x reference)
;     __device__ __forceinline__ void k_hook(int t, int wid) const {
;         if (t == tgate) {
;             if (wid == 0) {
;                 unsigned sp = 0;
;                 while ((unsigned)__builtin_amdgcn_readfirstlane(__hip_atomic_load(flag, __ATOMIC_RELAXED, __HIP_MEMORY_SCOPE_AGENT)) != epoch) { __builtin_amdgcn_s_sleep(2); if (++sp > (1u << 22)) break; }
;                 __builtin_amdgcn_fence(__ATOMIC_ACQUIRE, "agent");
;                 asm volatile("s_waitcnt vmcnt(0)" ::: "memory");
;             }
;             asm volatile("" ::: "memory"); __builtin_amdgcn_s_barrier(); asm volatile("" ::: "memory");
;         }
.LBB0_495:
	s_nop 0
	s_waitcnt vmcnt(0)

;     __device__ __forceinline__ void k_hook(int t, int wid) const {
;         if (t == tgate) {
;             if (wid == 0) {
;                 unsigned sp = 0;
;                 while ((unsigned)__builtin_amdgcn_readfirstlane(__hip_atomic_load(flag, __ATOMIC_RELAXED, __HIP_MEMORY_SCOPE_AGENT)) != epoch) { __builtin_amdgcn_s_sleep(2); if (++sp > (1u << 22)) break; }
;                 __builtin_amdgcn_fence(__ATOMIC_ACQUIRE, "agent");
;                 asm volatile("s_waitcnt vmcnt(0)" ::: "memory");
;             }
;             asm volatile("" ::: "memory"); __builtin_amdgcn_s_barrier(); asm volatile("" ::: "memory");
;         }
.LBB0_498:
	s_cmp_lg_u32 s41, 6
	s_cbranch_scc1 .LBB0_497
	s_andn2_b64 vcc, exec, s[22:23]
	s_cbranch_vccnz .LBB0_496
	buffer_inv sc1
	s_mov_b32 s28, 0x400001
	s_branch .LBB0_502
